# attention main loop: waves 4-7 run a reordered copy (softmax finish, PV, then QK^T) so the two waves per SIMD are out of phase
# baseline (speedup 1.0000x reference)
; #define VMW() asm volatile("s_waitcnt vmcnt(0)" ::: "memory")
; #define SLOAD_H(Kp, Vp, k0) do { S.st_v0 = load8(ROW(Vp, k0, sr)); S.st_v1 = load8(ROW(Vp, k0, 32 + sr)); S.st_k0 = load8(ROW(Kp, k0, sr)); S.st_k1 = load8(ROW(Kp, k0, 32 + sr)); } while (0)
; #define SWRITE_HK(bf) do { *(bf16x8*)(K_lds + (bf) * SHM_K + kws) = S.st_k0; *(bf16x8*)(K_lds + (bf) * SHM_K + kws + 32 * 256) = S.st_k1; } while (0)
; #define WSP(off) ((bf16*)((unsigned char*)kargp(25) + (off)))
; __device__ __forceinline__ void attn_prime(const BlockRef& cur, char* lds, Seam& S) {
;     int tid_ = threadIdx.x; asm volatile("" : "+v"(tid_));
;     const int tid = tid_, wid = __builtin_amdgcn_readfirstlane(tid >> 6), lane = tid & 63, r32 = lane & 31, hi = lane >> 5;
;     const int sr = tid >> 4, sc = (tid & 15) * 8, kws = KSWZ(sr, sc * 2); char* K_lds = lds + 2 * SHM_V;
;     for (int d0 = 0; d0 < 8; ++d0) S.qr[d0] = load8(cur.Q + (size_t)(wid * QBLK + r32) * D + d0 * 16 + hi * 8);
;     SLOAD_H(cur.K, cur.V, 0); VMW(); SWRITE_HK(0);
;     __syncthreads();
; }
; __global__ void __launch_bounds__(NTHR, 2) mega_fwd(Args args) {
;     ...
;         bf16* QH = WSP(WS_QH); bf16* KH = WSP(WS_KH); bf16* VH = WSP(WS_VH); bf16* O16 = WSP(WS_O16); bf16* OA = WSP(WS_OA);
;         att::Seam S;
;         const int NSI = BATCH * 4 * 16;
;         if (vcu < NSI) {
;             int si = vcu, sub = 0;
;     ...
;             att::BlockRef cur, nxt; MKREF(cur, si, sub);
;             att::attn_prime(cur, (char*)lds, S);
.LBB0_314:
	s_or_b64 exec, exec, s[14:15]
	s_nop 0
	s_nop 0
	s_nop 0
	s_nop 0
	s_nop 0
	s_nop 0
	s_nop 0
	s_nop 0
	s_nop 0
	s_nop 0
	s_nop 0
	s_nop 0
	s_nop 0
	s_nop 0
	s_nop 0
	s_nop 0
	s_nop 0
	s_nop 0
	s_nop 0
	s_nop 0
	s_nop 0
	s_nop 0
	s_nop 0
	s_nop 0
	s_nop 0
	s_waitcnt lgkmcnt(0)
	s_barrier
	s_movk_i32 s13, 0x100
	s_cmpk_lt_i32 s66, 0x100
	s_mov_b64 s[22:23], s[0:1]
	v_readfirstlane_b32 s24, v192
	s_mov_b64 s[20:21], s[0:1]
	s_mov_b64 s[18:19], s[0:1]
	s_mov_b64 s[14:15], s[0:1]
	s_mov_b64 s[16:17], s[0:1]
	s_cbranch_scc0 .LBB0_488
	s_load_dwordx2 s[22:23], s[22:23], 0xc8
	v_mov_b32_e32 v1, v216
	s_load_dwordx2 s[20:21], s[20:21], 0xc8
	v_mov_b32_e32 v195, 0
	s_load_dwordx2 s[18:19], s[18:19], 0xc8
	s_waitcnt lgkmcnt(0)
	s_add_u32 s25, s22, 0x2f800000
	s_addc_u32 s26, s23, 0
	s_load_dwordx2 s[14:15], s[14:15], 0xc8
	s_add_u32 s27, s20, 0x33800000
	s_addc_u32 s28, s21, 0
	s_add_u32 s30, s18, 0x37800000
	s_addc_u32 s31, s19, 0
	s_waitcnt lgkmcnt(0)
	s_add_u32 s14, s14, 0xf800000
	s_addc_u32 s15, s15, 0
	s_bfe_u32 s20, s66, 0x20004
	s_ashr_i32 s21, s66, 6
	s_lshl_b32 s18, s20, 15
	s_lshl_b32 s19, s21, 17
	s_or_b32 s18, s18, s19
	s_lshl_b32 s19, s66, 8
	s_and_b32 s19, s19, 0xf00
	s_lshl_b32 s20, s20, 14
	s_lshl_b32 s21, s21, 16
	s_xor_b32 s29, s19, 0x1f00
	s_or_b32 s20, s20, s21
	s_or_b32 s18, s18, s29
	s_or_b32 s22, s20, s29
	s_ashr_i32 s19, s18, 31
	s_ashr_i32 s23, s22, 31
	s_lshl_b64 s[18:19], s[18:19], 8
	s_ashr_i32 s21, s20, 31
	s_lshl_b64 s[22:23], s[22:23], 8
	s_add_u32 s36, s25, s22
	s_addc_u32 s37, s26, s23
	s_lshl_b64 s[20:21], s[20:21], 8
	s_add_u32 s70, s27, s20
	s_addc_u32 s71, s28, s21
	s_add_u32 s72, s30, s20
	s_addc_u32 s73, s31, s21
	s_load_dwordx2 s[16:17], s[16:17], 0xc8
	s_add_u32 s22, s14, s18
	s_addc_u32 s23, s15, s19
	v_readfirstlane_b32 s18, v1
	s_ashr_i32 s18, s18, 1
	s_movk_i32 s19, 0xffe0
	v_mov_b32_e32 v2, s18
	v_bfi_b32 v2, s19, v2, v1
	v_ashrrev_i32_e32 v3, 31, v2
	v_lshlrev_b64 v[2:3], 8, v[2:3]
	s_waitcnt vmcnt(32)
	v_lshrrev_b32_e32 v4, 1, v1
	v_lshl_add_u64 v[2:3], s[36:37], 0, v[2:3]
	v_and_b32_e32 v194, 16, v4
	v_lshl_add_u64 v[2:3], v[2:3], 0, v[194:195]
	global_load_dwordx4 v[156:159], v[2:3], off
	global_load_dwordx4 v[152:155], v[2:3], off offset:32
	global_load_dwordx4 v[148:151], v[2:3], off offset:64
	global_load_dwordx4 v[144:147], v[2:3], off offset:96
	global_load_dwordx4 v[140:143], v[2:3], off offset:128
	global_load_dwordx4 v[136:139], v[2:3], off offset:160
	global_load_dwordx4 v[132:135], v[2:3], off offset:192
	global_load_dwordx4 v[128:131], v[2:3], off offset:224
	v_ashrrev_i32_e32 v2, 4, v1
	v_lshlrev_b32_e32 v3, 4, v1
	s_movk_i32 s18, 0xf0
	v_and_b32_e32 v1, 0x70, v1
	v_and_b32_e32 v194, 0xf0, v3
	v_bitop3_b32 v1, v3, v1, s18 bitop3:0x6c
	v_ashrrev_i32_e32 v3, 31, v2
	s_waitcnt vmcnt(37)
	v_lshlrev_b32_e32 v10, 8, v2
	v_lshlrev_b64 v[2:3], 8, v[2:3]
	v_lshl_add_u64 v[4:5], s[72:73], 0, v[2:3]
	s_mov_b64 s[18:19], 0x2000
	v_lshl_add_u64 v[4:5], v[4:5], 0, v[194:195]
	v_lshl_add_u64 v[6:7], v[2:3], 0, s[18:19]
	global_load_dwordx4 v[96:99], v[4:5], off
	v_lshl_add_u64 v[4:5], s[72:73], 0, v[6:7]
	v_lshl_add_u64 v[2:3], s[70:71], 0, v[2:3]
	v_lshl_add_u64 v[4:5], v[4:5], 0, v[194:195]
	v_lshl_add_u64 v[2:3], v[2:3], 0, v[194:195]
	v_lshl_add_u64 v[6:7], s[70:71], 0, v[6:7]
	global_load_dwordx4 v[100:103], v[4:5], off
	v_lshl_add_u64 v[6:7], v[6:7], 0, v[194:195]
	global_load_dwordx4 v[2:5], v[2:3], off
	v_writelane_b32 v254, s25, 53
	global_load_dwordx4 v[6:9], v[6:7], off
	v_add3_u32 v1, 0, v10, v1
	v_and_b32_e32 v255, 0x800, v10
	v_lshrrev_b32_e32 v255, 4, v255
	v_xor_b32_e32 v1, v1, v255
	v_writelane_b32 v254, s26, 54
	s_waitcnt vmcnt(0)
	v_writelane_b32 v254, s27, 55
	s_ashr_i32 s18, s24, 3
	v_writelane_b32 v254, s28, 56
	s_and_b32 s18, s18, -8
	v_and_b32_e32 v0, 63, v192
	v_writelane_b32 v254, s30, 57
	s_cmpk_lt_i32 s18, 0x200
	v_writelane_b32 v254, s31, 58
	s_mov_b32 s48, 0
	v_bfe_u32 v193, v192, 4, 2
	s_cselect_b64 s[24:25], -1, 0
	s_mov_b32 s67, 0x41000000
	s_mov_b32 s26, 0x3e0293ee
	v_mbcnt_hi_u32_b32 v205, -1, v217
	v_lshlrev_b32_e32 v214, 2, v0
	s_mov_b32 s28, 0x3f4ccccd
	s_mov_b32 s64, 0x200000
	s_mov_b32 s65, 0x400000
	s_mov_b32 s27, 0x600000
	v_mov_b32_e32 v218, 0x358637bd
	s_mov_b32 s47, 0xf800000
	v_mov_b32_e32 v219, 0x260
	v_mov_b32_e32 v220, 0xff800000
	v_mov_b32_e32 v221, 0xf149f2ca
	s_mov_b32 s77, 0
	v_writelane_b32 v254, s18, 59
	s_waitcnt vmcnt(1)
	ds_write_b128 v1, v[2:5] offset:32768
	s_waitcnt vmcnt(0)
	ds_write_b128 v1, v[6:9] offset:40960
	v_lshlrev_b32_e32 v1, 3, v192
	v_and_b32_e32 v2, 0x78, v1
	v_lshlrev_b32_e32 v194, 1, v2
	s_waitcnt lgkmcnt(0)
	v_lshl_add_u64 v[4:5], s[16:17], 0, v[194:195]
	s_mov_b64 s[16:17], 0x17800000
	v_lshl_add_u64 v[196:197], s[14:15], 0, v[194:195]
	v_lshl_add_u64 v[198:199], v[4:5], 0, s[16:17]
	v_lshlrev_b32_e32 v215, 2, v2
	s_barrier
	s_branch .LBB0_317

; __device__ __forceinline__ void attn_block(const BlockRef& cur, const BlockRef& nxt, char* lds, Seam& S) {
;     ...
;     for (int t = 1; t + 1 < NT; t += 2) {
;         HALF_STEP(pB0, pB1, mnB, alB, pA0, pA1, alA, t, 1, 0, 0);
;         HALF_STEP(pA0, pA1, mnA, alA, pB0, pB1, alB, t + 1, 0, 1, 1);
.LBB0_320:
	v_readfirstlane_b32 s51, v222
	s_bitcmp1_b32 s51, 8
	s_cbranch_scc1 .Lmy_B_head

; __device__ __forceinline__ void finishSM(f32x16& p0, f32x16& p1, float alpha, float& l_reg, bf16x8& pa0, bf16x8& pa1, bf16x8& pa2, bf16x8& pa3) {
;     for (int r = 0; r < 16; ++r) p1[r] = __builtin_amdgcn_exp2f(p1[r]);
;     float ps = 0; for (int r = 0; r < 16; ++r) ps += p0[r]; for (int r = 0; r < 16; ++r) ps += p1[r];
;     { auto rr = __builtin_amdgcn_permlane32_swap(__float_as_uint(ps), __float_as_uint(ps), false, false);
;       ps = __uint_as_float(rr[0]) + __uint_as_float(rr[1]); }
;     l_reg = l_reg * alpha + ps;
;     ...
;     PK4(p0, 0, pa0); PK4(p0, 8, pa1); PK4(p1, 0, pa2); PK4(p1, 8, pa3);
;     ...
; }
; template <int KB>
; __device__ __forceinline__ void qkt(f32x16& p0, f32x16& p1, const char* K_lds, int r32, int hi, const bf16x8* qr) {
;     p0 = f32x16{}; p1 = f32x16{};
;     const char* kb[4];
; #pragma unroll
;     for (int dd = 0; dd < 4; ++dd) kb[dd] = K_lds + KB * SHM_K + KSWZ(r32, (dd * 16 + hi * 8) * 2);
; #pragma unroll
;     for (int d0 = 0; d0 < 8; ++d0) { const char* a = kb[d0 & 3] + (d0 >> 2) * 128;
;         bf16x8 b0 = *reinterpret_cast<const bf16x8*>(a);
;         bf16x8 b1 = *reinterpret_cast<const bf16x8*>(a + 32 * 256);
;         p0 = __builtin_amdgcn_mfma_f32_32x32x16_bf16(b0, qr[d0], p0, 0, 0, 0);
;         p1 = __builtin_amdgcn_mfma_f32_32x32x16_bf16(b1, qr[d0], p1, 0, 0, 0); }
; }
; template <int VB>
; __device__ __forceinline__ void pv_tile(f32x16* o, int vb0, bf16x8 pa0, bf16x8 pa1, bf16x8 pa2, bf16x8 pa3) {
;     ...
;     PV_D0(0); PV_D0(1); PV_D0(2); PV_D0(3);
;     ...
; }
.Lmy_B_head:
	ds_read_b64_tr_b16 v[238:239], v225 offset:0
	ds_read_b64_tr_b16 v[240:241], v225 offset:0x800
	ds_read_b64_tr_b16 v[242:243], v225 offset:0x1000
	ds_read_b64_tr_b16 v[244:245], v225 offset:0x1800
	ds_read_b64_tr_b16 v[246:247], v225 offset:0x2000
	ds_read_b64_tr_b16 v[248:249], v225 offset:0x2800
	ds_read_b64_tr_b16 v[250:251], v225 offset:0x3000
	ds_read_b64_tr_b16 v[252:253], v225 offset:0x3800
	v_exp_f32_e32 v104, v126
	v_exp_f32_e32 v105, v127
	v_exp_f32_e32 v106, v122
	v_exp_f32_e32 v107, v123
	v_exp_f32_e32 v108, v118
	v_exp_f32_e32 v109, v119
	v_exp_f32_e32 v110, v116
	v_exp_f32_e32 v111, v117
	v_exp_f32_e32 v112, v112
	v_exp_f32_e32 v113, v113
	v_exp_f32_e32 v116, v124
	v_exp_f32_e32 v117, v125
	v_exp_f32_e32 v118, v120
	v_exp_f32_e32 v119, v121
	v_exp_f32_e32 v114, v114
	v_exp_f32_e32 v115, v115
	v_add_f32_e32 v96, 0, v169
	v_add_f32_e32 v96, v170, v96
	v_add_f32_e32 v96, v171, v96
	v_add_f32_e32 v96, v173, v96
	v_add_f32_e32 v96, v174, v96
	v_add_f32_e32 v96, v177, v96
	v_add_f32_e32 v96, v172, v96
	v_add_f32_e32 v96, v175, v96
	v_add_f32_e32 v96, v161, v96
	v_add_f32_e32 v96, v163, v96
	v_add_f32_e32 v96, v164, v96
	v_add_f32_e32 v96, v167, v96
	v_add_f32_e32 v96, v162, v96
	v_add_f32_e32 v96, v165, v96
	v_add_f32_e32 v96, v166, v96
	v_add_f32_e32 v96, v168, v96
	v_add_f32_e32 v96, v104, v96
	v_add_f32_e32 v96, v105, v96
	v_add_f32_e32 v96, v106, v96
	v_add_f32_e32 v96, v107, v96
	v_add_f32_e32 v96, v108, v96
	v_add_f32_e32 v96, v109, v96
	v_add_f32_e32 v96, v110, v96
	v_add_f32_e32 v96, v111, v96
	v_add_f32_e32 v96, v112, v96
	v_add_f32_e32 v96, v113, v96
	v_add_f32_e32 v96, v116, v96
	v_add_f32_e32 v96, v117, v96
	v_add_f32_e32 v96, v118, v96
	v_add_f32_e32 v96, v119, v96
	v_add_f32_e32 v96, v114, v96
	v_add_f32_e32 v194, v115, v96
	v_mov_b32_e32 v234, v194
	v_cvt_pk_bf16_f32 v96, v169, v170
	v_cvt_pk_bf16_f32 v97, v171, v173
	v_cvt_pk_bf16_f32 v98, v174, v177
	v_cvt_pk_bf16_f32 v99, v172, v175
	v_permlane32_swap_b32_e32 v194, v234
	v_permlane32_swap_b32_e32 v96, v98
	v_permlane32_swap_b32_e32 v97, v99
	v_cvt_pk_bf16_f32 v100, v161, v163
	v_cvt_pk_bf16_f32 v101, v164, v167
	v_cvt_pk_bf16_f32 v102, v162, v165
	v_cvt_pk_bf16_f32 v103, v166, v168
	v_cvt_pk_bf16_f32 v104, v104, v105
	v_cvt_pk_bf16_f32 v105, v106, v107
	v_cvt_pk_bf16_f32 v106, v108, v109
	v_cvt_pk_bf16_f32 v107, v110, v111
	v_cvt_pk_bf16_f32 v108, v112, v113
	v_cvt_pk_bf16_f32 v109, v116, v117
	v_cvt_pk_bf16_f32 v110, v118, v119
	v_cvt_pk_bf16_f32 v111, v114, v115
	v_permlane32_swap_b32_e32 v100, v102
	v_permlane32_swap_b32_e32 v101, v103
	v_permlane32_swap_b32_e32 v104, v106
	v_permlane32_swap_b32_e32 v105, v107
	v_permlane32_swap_b32_e32 v108, v110
	v_permlane32_swap_b32_e32 v109, v111
	v_add_u32_e32 v212, s50, v202
	v_ashrrev_i32_e32 v213, 31, v212
	v_add_u32_e32 v116, 32, v212
	v_lshlrev_b64 v[112:113], 8, v[212:213]
	v_ashrrev_i32_e32 v117, 31, v116
	v_lshl_add_u64 v[114:115], v[208:209], 0, v[112:113]
	v_lshlrev_b64 v[116:117], 8, v[116:117]
	v_lshl_add_u64 v[112:113], v[210:211], 0, v[112:113]
	v_lshl_add_u64 v[118:119], v[208:209], 0, v[116:117]
	global_load_dwordx4 v[160:163], v[114:115], off
	global_load_dwordx4 v[164:167], v[118:119], off
	v_lshl_add_u64 v[114:115], v[210:211], 0, v[116:117]
	global_load_dwordx4 v[168:171], v[112:113], off
	global_load_dwordx4 v[172:175], v[114:115], off
	s_waitcnt lgkmcnt(0)
	s_nop 0
	v_mfma_f32_32x32x16_bf16 v[0:15], v[96:99], v[238:241], v[0:15]
	ds_read_b64_tr_b16 v[112:113], v225 offset:0x200
	ds_read_b64_tr_b16 v[114:115], v225 offset:0xa00
	v_mfma_f32_32x32x16_bf16 v[0:15], v[100:103], v[242:245], v[0:15]
	ds_read_b64_tr_b16 v[116:117], v225 offset:0x1200
	ds_read_b64_tr_b16 v[118:119], v225 offset:0x1a00
	v_mfma_f32_32x32x16_bf16 v[0:15], v[104:107], v[246:249], v[0:15]
	ds_read_b64_tr_b16 v[120:121], v225 offset:0x2200
	ds_read_b64_tr_b16 v[122:123], v225 offset:0x2a00
	v_mfma_f32_32x32x16_bf16 v[0:15], v[108:111], v[250:253], v[0:15]
	ds_read_b64_tr_b16 v[124:125], v225 offset:0x3200
	ds_read_b64_tr_b16 v[126:127], v225 offset:0x3a00
	s_waitcnt lgkmcnt(0)
	v_mfma_f32_32x32x16_bf16 v[48:63], v[96:99], v[112:115], v[48:63]
	ds_read_b64_tr_b16 v[112:113], v225 offset:0x400
	ds_read_b64_tr_b16 v[114:115], v225 offset:0xc00
	v_mfma_f32_32x32x16_bf16 v[48:63], v[100:103], v[116:119], v[48:63]
	ds_read_b64_tr_b16 v[116:117], v225 offset:0x1400
	ds_read_b64_tr_b16 v[118:119], v225 offset:0x1c00
	v_mfma_f32_32x32x16_bf16 v[48:63], v[104:107], v[120:123], v[48:63]
	ds_read_b64_tr_b16 v[120:121], v225 offset:0x2400
	ds_read_b64_tr_b16 v[122:123], v225 offset:0x2c00
	v_mfma_f32_32x32x16_bf16 v[48:63], v[108:111], v[124:127], v[48:63]
	ds_read_b64_tr_b16 v[124:125], v225 offset:0x3400
	ds_read_b64_tr_b16 v[126:127], v225 offset:0x3c00
	s_waitcnt lgkmcnt(0)
	v_mfma_f32_32x32x16_bf16 v[32:47], v[96:99], v[112:115], v[32:47]
	ds_read_b64_tr_b16 v[112:113], v225 offset:0x600
	ds_read_b64_tr_b16 v[114:115], v225 offset:0xe00
	v_mfma_f32_32x32x16_bf16 v[32:47], v[100:103], v[116:119], v[32:47]
	ds_read_b64_tr_b16 v[116:117], v225 offset:0x1600
	ds_read_b64_tr_b16 v[118:119], v225 offset:0x1e00
	v_mfma_f32_32x32x16_bf16 v[32:47], v[104:107], v[120:123], v[32:47]
	ds_read_b64_tr_b16 v[120:121], v225 offset:0x2600
	ds_read_b64_tr_b16 v[122:123], v225 offset:0x2e00
	v_mfma_f32_32x32x16_bf16 v[32:47], v[108:111], v[124:127], v[32:47]
	ds_read_b64_tr_b16 v[124:125], v225 offset:0x3600
	ds_read_b64_tr_b16 v[126:127], v225 offset:0x3e00
	s_waitcnt lgkmcnt(0)
	s_waitcnt vmcnt(0)
; __device__ __forceinline__ void partialSM(f32x16& p0, f32x16& p1, float& m_reg, float& mn, float& alpha) {
;     float pmax = p0[0]; for (int r = 1; r < 16; ++r) pmax = fmaxf(pmax, p0[r]); for (int r = 0; r < 16; ++r) pmax = fmaxf(pmax, p1[r]);
;     { auto rr = __builtin_amdgcn_permlane32_swap(__float_as_uint(pmax), __float_as_uint(pmax), false, false);
;       pmax = fmaxf(__uint_as_float(rr[0]), __uint_as_float(rr[1])); }
;     constexpr float C2 = 1.4426950408889634f * SCALE;
;     if (__builtin_expect(__all((pmax - m_reg) * SCALE <= THR), 1)) { mn = m_reg; alpha = 1.f; }
;     else { mn = fmaxf(m_reg, pmax); alpha = __builtin_amdgcn_exp2f((m_reg - mn) * C2); m_reg = mn; }
;     const float mnL = -mn * C2;
;     for (int r = 0; r < 16; ++r) p0[r] = fmaf(p0[r], C2, mnL); for (int r = 0; r < 16; ++r) p1[r] = fmaf(p1[r], C2, mnL);
;     for (int r = 0; r < 16; ++r) p0[r] = __builtin_amdgcn_exp2f(p0[r]);
; }
; template <int KB>
; __device__ __forceinline__ void qkt(f32x16& p0, f32x16& p1, const char* K_lds, int r32, int hi, const bf16x8* qr) {
;     p0 = f32x16{}; p1 = f32x16{};
;     const char* kb[4];
; #pragma unroll
;     for (int dd = 0; dd < 4; ++dd) kb[dd] = K_lds + KB * SHM_K + KSWZ(r32, (dd * 16 + hi * 8) * 2);
; #pragma unroll
;     for (int d0 = 0; d0 < 8; ++d0) { const char* a = kb[d0 & 3] + (d0 >> 2) * 128;
;         bf16x8 b0 = *reinterpret_cast<const bf16x8*>(a);
;         bf16x8 b1 = *reinterpret_cast<const bf16x8*>(a + 32 * 256);
;         p0 = __builtin_amdgcn_mfma_f32_32x32x16_bf16(b0, qr[d0], p0, 0, 0, 0);
;         p1 = __builtin_amdgcn_mfma_f32_32x32x16_bf16(b1, qr[d0], p1, 0, 0, 0); }
; }
	ds_write_b128 v231, v[160:163] offset:16384
	ds_write_b128 v232, v[164:167] offset:16384
	ds_write_b128 v226, v[168:171] offset:32768
	ds_write_b128 v226, v[172:175] offset:40960
	v_mfma_f32_32x32x16_bf16 v[16:31], v[96:99], v[112:115], v[16:31]
	v_mfma_f32_32x32x16_bf16 v[16:31], v[100:103], v[116:119], v[16:31]
	v_mfma_f32_32x32x16_bf16 v[16:31], v[104:107], v[120:123], v[16:31]
	v_mfma_f32_32x32x16_bf16 v[16:31], v[108:111], v[124:127], v[16:31]
	v_xor_b32_e32 v250, 0x80, v201
	v_xor_b32_e32 v251, 0x80, v230
	v_xor_b32_e32 v252, 0x80, v229
	v_xor_b32_e32 v253, 0x80, v207
	ds_read_b128 v[64:67], v201 offset:49152
	ds_read_b128 v[68:71], v201 offset:57344
	ds_read_b128 v[96:99], v230 offset:49152
	ds_read_b128 v[100:103], v230 offset:57344
	s_waitcnt lgkmcnt(3)
	v_mfma_f32_32x32x16_bf16 v[80:95], v[64:67], v[156:159], 0
	s_waitcnt lgkmcnt(2)
	v_mfma_f32_32x32x16_bf16 v[64:79], v[68:71], v[156:159], 0
	s_waitcnt lgkmcnt(1)
	v_mfma_f32_32x32x16_bf16 v[80:95], v[96:99], v[152:155], v[80:95]
	s_waitcnt lgkmcnt(0)
	v_mfma_f32_32x32x16_bf16 v[64:79], v[100:103], v[152:155], v[64:79]
	ds_read_b128 v[96:99], v229 offset:49152
	ds_read_b128 v[100:103], v229 offset:57344
	s_waitcnt lgkmcnt(1)
	v_mfma_f32_32x32x16_bf16 v[80:95], v[96:99], v[148:151], v[80:95]
	s_waitcnt lgkmcnt(0)
	v_mfma_f32_32x32x16_bf16 v[64:79], v[100:103], v[148:151], v[64:79]
	ds_read_b128 v[96:99], v207 offset:49152
	ds_read_b128 v[100:103], v207 offset:57344
	s_waitcnt lgkmcnt(1)
	v_mfma_f32_32x32x16_bf16 v[80:95], v[96:99], v[144:147], v[80:95]
	s_waitcnt lgkmcnt(0)
	v_mfma_f32_32x32x16_bf16 v[64:79], v[100:103], v[144:147], v[64:79]
	ds_read_b128 v[96:99], v250 offset:49152
	ds_read_b128 v[100:103], v250 offset:57344
	s_waitcnt lgkmcnt(1)
	v_mfma_f32_32x32x16_bf16 v[80:95], v[96:99], v[140:143], v[80:95]
	s_waitcnt lgkmcnt(0)
	v_mfma_f32_32x32x16_bf16 v[64:79], v[100:103], v[140:143], v[64:79]
	ds_read_b128 v[96:99], v251 offset:49152
	ds_read_b128 v[100:103], v251 offset:57344
	s_waitcnt lgkmcnt(1)
	v_mfma_f32_32x32x16_bf16 v[80:95], v[96:99], v[136:139], v[80:95]
	s_waitcnt lgkmcnt(0)
	v_mfma_f32_32x32x16_bf16 v[64:79], v[100:103], v[136:139], v[64:79]
	ds_read_b128 v[96:99], v252 offset:49152
	ds_read_b128 v[100:103], v252 offset:57344
	s_waitcnt lgkmcnt(1)
	v_mfma_f32_32x32x16_bf16 v[80:95], v[96:99], v[132:135], v[80:95]
	s_waitcnt lgkmcnt(0)
	v_mfma_f32_32x32x16_bf16 v[64:79], v[100:103], v[132:135], v[64:79]
	ds_read_b128 v[96:99], v253 offset:49152
	ds_read_b128 v[100:103], v253 offset:57344
	s_waitcnt lgkmcnt(1)
	v_mfma_f32_32x32x16_bf16 v[80:95], v[96:99], v[128:131], v[80:95]
	s_waitcnt lgkmcnt(0)
	v_mfma_f32_32x32x16_bf16 v[64:79], v[100:103], v[128:131], v[64:79]
	s_nop 15
	s_sub_i32 s40, s50, 64
	s_cmp_gt_i32 s40, s49
	s_cbranch_scc0 .Lmy_B_nomask1
	v_mov_b32_e32 v64, v220
	v_mov_b32_e32 v65, v220
	v_mov_b32_e32 v66, v220
	v_mov_b32_e32 v67, v220
	v_mov_b32_e32 v68, v220
	v_mov_b32_e32 v69, v220
	v_mov_b32_e32 v70, v220
	v_mov_b32_e32 v71, v220
	v_mov_b32_e32 v72, v220
	v_mov_b32_e32 v73, v220
	v_mov_b32_e32 v74, v220
	v_mov_b32_e32 v75, v220
	v_mov_b32_e32 v76, v220
	v_mov_b32_e32 v77, v220
	v_mov_b32_e32 v78, v220
	v_mov_b32_e32 v79, v220
	v_mov_b32_e32 v80, v220
	v_mov_b32_e32 v81, v220
	v_mov_b32_e32 v82, v220
	v_mov_b32_e32 v83, v220
	v_mov_b32_e32 v84, v220
	v_mov_b32_e32 v85, v220
	v_mov_b32_e32 v86, v220
	v_mov_b32_e32 v87, v220
	v_mov_b32_e32 v88, v220
	v_mov_b32_e32 v89, v220
	v_mov_b32_e32 v90, v220
	v_mov_b32_e32 v91, v220
	v_mov_b32_e32 v92, v220
	v_mov_b32_e32 v93, v220
	v_mov_b32_e32 v94, v220
	v_mov_b32_e32 v95, v220
.Lmy_B_nomask1:
	s_nop 0
	v_mov_b32_e32 v97, v81
	v_mov_b32_e32 v98, v80
	v_mov_b32_e32 v96, v82
	v_mov_b32_e32 v81, v78
	v_mov_b32_e32 v82, v77
	v_max_f32_e32 v77, v97, v97
	v_max_f32_e32 v78, v98, v98
	v_max_f32_e32 v77, v78, v77
	v_max3_f32 v77, v77, v96, v83
	v_max3_f32 v77, v77, v84, v85
	v_max3_f32 v77, v77, v86, v87
	v_max3_f32 v77, v77, v88, v89
	v_max3_f32 v77, v77, v90, v91
	v_max3_f32 v77, v77, v92, v93
	v_max3_f32 v77, v77, v94, v95
	s_nop 0
	v_max3_f32 v77, v77, v64, v65
	v_max3_f32 v77, v77, v66, v67
	v_max3_f32 v77, v77, v68, v69
	v_max3_f32 v77, v77, v70, v71
	v_max3_f32 v77, v77, v72, v73
	v_max3_f32 v77, v77, v74, v75
	v_mov_b32_e32 v80, v79
	v_max3_f32 v77, v77, v76, v82
	v_max3_f32 v77, v77, v81, v80
	s_nop 0
	v_mov_b32_e32 v78, v77
	s_nop 1
	v_permlane32_swap_b32_e32 v77, v78
	v_max_f32_e32 v78, v78, v78
	v_max_f32_e32 v77, v77, v77
	v_max_f32_e32 v77, v77, v78
	v_sub_f32_e32 v78, v77, v176
	v_mul_f32_e32 v78, 0x3db504f3, v78
	v_cmp_ge_f32_e32 vcc, s67, v78
	v_max_f32_e32 v78, v176, v176
	v_max_f32_e32 v77, v78, v77
	s_nop 0
	v_sub_f32_e32 v78, v176, v77
	v_mul_f32_e32 v78, 0x3e0293ee, v78
	v_exp_f32_e32 v78, v78
	s_cmp_eq_u64 vcc, exec
	s_cselect_b64 s[40:41], -1, 0
	v_cndmask_b32_e64 v213, v78, 1.0, s[40:41]
	v_cmp_gt_f32_e32 vcc, 1.0, v213
	s_cbranch_vccz .Lmy_B324
	s_and_saveexec_b64 s[42:43], s[38:39]
	ds_write_b32 v227, v213 offset:128
	s_or_b64 exec, exec, s[42:43]
	s_waitcnt lgkmcnt(0)
	v_add_u32_e32 v78, s69, v200
	ds_read_b128 v[100:103], v78 offset:224
	ds_read_b128 v[104:107], v78 offset:192
	ds_read_b128 v[108:111], v78 offset:160
	ds_read_b128 v[112:115], v78 offset:128
	s_waitcnt lgkmcnt(3)
	v_pk_mul_f32 v[12:13], v[12:13], v[100:101]
	s_waitcnt lgkmcnt(2)
	v_pk_mul_f32 v[8:9], v[8:9], v[104:105]
	s_waitcnt lgkmcnt(1)
	v_pk_mul_f32 v[4:5], v[4:5], v[108:109]
	v_pk_mul_f32 v[14:15], v[14:15], v[102:103]
	v_pk_mul_f32 v[10:11], v[10:11], v[106:107]
	v_pk_mul_f32 v[6:7], v[6:7], v[110:111]
	s_waitcnt lgkmcnt(0)
	v_pk_mul_f32 v[2:3], v[2:3], v[114:115]
	v_pk_mul_f32 v[0:1], v[0:1], v[112:113]
	v_pk_mul_f32 v[60:61], v[60:61], v[100:101]
	v_pk_mul_f32 v[56:57], v[56:57], v[104:105]
	v_pk_mul_f32 v[52:53], v[52:53], v[108:109]
	v_pk_mul_f32 v[62:63], v[62:63], v[102:103]
	v_pk_mul_f32 v[58:59], v[58:59], v[106:107]
	v_pk_mul_f32 v[54:55], v[54:55], v[110:111]
	v_pk_mul_f32 v[50:51], v[50:51], v[114:115]
	v_pk_mul_f32 v[48:49], v[48:49], v[112:113]
	v_pk_mul_f32 v[44:45], v[44:45], v[100:101]
	v_pk_mul_f32 v[40:41], v[40:41], v[104:105]
	v_pk_mul_f32 v[36:37], v[36:37], v[108:109]
	v_pk_mul_f32 v[46:47], v[46:47], v[102:103]
	v_pk_mul_f32 v[42:43], v[42:43], v[106:107]
	v_pk_mul_f32 v[38:39], v[38:39], v[110:111]
	v_pk_mul_f32 v[34:35], v[34:35], v[114:115]
	v_pk_mul_f32 v[32:33], v[32:33], v[112:113]
	v_pk_mul_f32 v[28:29], v[28:29], v[100:101]
	v_pk_mul_f32 v[24:25], v[24:25], v[104:105]
	v_pk_mul_f32 v[20:21], v[20:21], v[108:109]
	v_pk_mul_f32 v[30:31], v[30:31], v[102:103]
	v_pk_mul_f32 v[26:27], v[26:27], v[106:107]
	v_pk_mul_f32 v[22:23], v[22:23], v[110:111]
	v_pk_mul_f32 v[18:19], v[18:19], v[114:115]
	v_pk_mul_f32 v[16:17], v[16:17], v[112:113]
; __device__ __forceinline__ void partialSM(f32x16& p0, f32x16& p1, float& m_reg, float& mn, float& alpha) {
;     ...
;     if (__builtin_expect(__all((pmax - m_reg) * SCALE <= THR), 1)) { mn = m_reg; alpha = 1.f; }
;     else { mn = fmaxf(m_reg, pmax); alpha = __builtin_amdgcn_exp2f((m_reg - mn) * C2); m_reg = mn; }
;     const float mnL = -mn * C2;
;     for (int r = 0; r < 16; ++r) p0[r] = fmaf(p0[r], C2, mnL); for (int r = 0; r < 16; ++r) p1[r] = fmaf(p1[r], C2, mnL);
;     for (int r = 0; r < 16; ++r) p0[r] = __builtin_amdgcn_exp2f(p0[r]);
; }
; __device__ __forceinline__ void finishSM(f32x16& p0, f32x16& p1, float alpha, float& l_reg, bf16x8& pa0, bf16x8& pa1, bf16x8& pa2, bf16x8& pa3) {
;     for (int r = 0; r < 16; ++r) p1[r] = __builtin_amdgcn_exp2f(p1[r]);
;     float ps = 0; for (int r = 0; r < 16; ++r) ps += p0[r]; for (int r = 0; r < 16; ++r) ps += p1[r];
;     { auto rr = __builtin_amdgcn_permlane32_swap(__float_as_uint(ps), __float_as_uint(ps), false, false);
;       ps = __uint_as_float(rr[0]) + __uint_as_float(rr[1]); }
;     l_reg = l_reg * alpha + ps;
;     ...
;     PK4(p0, 0, pa0); PK4(p0, 8, pa1); PK4(p1, 0, pa2); PK4(p1, 8, pa3);
;     ...
; }
.Lmy_B324:
	v_cndmask_b32_e64 v235, v77, v176, s[40:41]
	v_mul_f32_e32 v176, 0xbe0293ee, v235
	v_fmamk_f32 v77, v98, 0x3e0293ee, v176
	v_fmamk_f32 v78, v97, 0x3e0293ee, v176
	v_fmamk_f32 v79, v96, 0x3e0293ee, v176
	v_fmamk_f32 v96, v83, 0x3e0293ee, v176
	v_fmamk_f32 v97, v84, 0x3e0293ee, v176
	v_fmamk_f32 v98, v85, 0x3e0293ee, v176
	v_fmamk_f32 v99, v86, 0x3e0293ee, v176
	v_fmamk_f32 v100, v87, 0x3e0293ee, v176
	v_fmamk_f32 v101, v88, 0x3e0293ee, v176
	v_fmamk_f32 v102, v89, 0x3e0293ee, v176
	v_fmamk_f32 v103, v90, 0x3e0293ee, v176
	v_fmamk_f32 v104, v91, 0x3e0293ee, v176
	v_fmamk_f32 v105, v92, 0x3e0293ee, v176
	v_fmamk_f32 v106, v93, 0x3e0293ee, v176
	v_fmamk_f32 v107, v94, 0x3e0293ee, v176
	v_fmamk_f32 v108, v95, 0x3e0293ee, v176
	v_fmamk_f32 v83, v64, 0x3e0293ee, v176
	v_fmamk_f32 v84, v65, 0x3e0293ee, v176
	v_fmamk_f32 v93, v66, 0x3e0293ee, v176
	v_fmamk_f32 v94, v67, 0x3e0293ee, v176
	v_fmamk_f32 v95, v68, 0x3e0293ee, v176
	v_fmamk_f32 v85, v69, 0x3e0293ee, v176
	v_fmamk_f32 v86, v70, 0x3e0293ee, v176
	v_fmamk_f32 v87, v71, 0x3e0293ee, v176
	v_fmamk_f32 v88, v72, 0x3e0293ee, v176
	v_fmamk_f32 v89, v73, 0x3e0293ee, v176
	v_fmamk_f32 v90, v74, 0x3e0293ee, v176
	v_fmamk_f32 v91, v75, 0x3e0293ee, v176
	v_fmamk_f32 v92, v76, 0x3e0293ee, v176
	v_exp_f32_e32 v64, v77
	v_exp_f32_e32 v65, v78
	v_exp_f32_e32 v66, v79
	v_exp_f32_e32 v67, v96
	v_exp_f32_e32 v68, v97
	v_exp_f32_e32 v69, v98
	v_exp_f32_e32 v70, v99
	v_exp_f32_e32 v71, v100
	v_exp_f32_e32 v72, v101
	v_exp_f32_e32 v73, v102
	v_exp_f32_e32 v74, v103
	v_exp_f32_e32 v75, v104
	v_exp_f32_e32 v76, v105
	v_exp_f32_e32 v77, v106
	v_exp_f32_e32 v78, v107
	v_exp_f32_e32 v79, v108
	v_fmamk_f32 v177, v82, 0x3e0293ee, v176
	v_fmamk_f32 v178, v81, 0x3e0293ee, v176
	v_fmac_f32_e32 v176, 0x3e0293ee, v80
	s_waitcnt lgkmcnt(0)
	s_barrier
	ds_read_b64_tr_b16 v[238:239], v225 offset:0x4000
	ds_read_b64_tr_b16 v[240:241], v225 offset:0x4800
	ds_read_b64_tr_b16 v[242:243], v225 offset:0x5000
	ds_read_b64_tr_b16 v[244:245], v225 offset:0x5800
	ds_read_b64_tr_b16 v[246:247], v225 offset:0x6000
	ds_read_b64_tr_b16 v[248:249], v225 offset:0x6800
	ds_read_b64_tr_b16 v[250:251], v225 offset:0x7000
	ds_read_b64_tr_b16 v[252:253], v225 offset:0x7800
	v_exp_f32_e32 v81, v84
	v_exp_f32_e32 v84, v95
	v_exp_f32_e32 v95, v176
	v_add_f32_e32 v176, 0, v64
	v_add_f32_e32 v176, v65, v176
	v_add_f32_e32 v176, v66, v176
	v_add_f32_e32 v176, v67, v176
	v_add_f32_e32 v176, v68, v176
	v_add_f32_e32 v176, v69, v176
	v_add_f32_e32 v176, v70, v176
	v_add_f32_e32 v176, v71, v176
	v_add_f32_e32 v176, v72, v176
	v_add_f32_e32 v176, v73, v176
	v_add_f32_e32 v176, v74, v176
	v_add_f32_e32 v176, v75, v176
	v_exp_f32_e32 v80, v83
	v_add_f32_e32 v176, v76, v176
	v_add_f32_e32 v176, v77, v176
	v_exp_f32_e32 v82, v93
	v_add_f32_e32 v176, v78, v176
	v_exp_f32_e32 v83, v94
	v_add_f32_e32 v176, v79, v176
	v_add_f32_e32 v176, v80, v176
	v_exp_f32_e32 v85, v85
	v_add_f32_e32 v176, v81, v176
	v_exp_f32_e32 v86, v86
	v_add_f32_e32 v176, v82, v176
	v_exp_f32_e32 v87, v87
	v_add_f32_e32 v176, v83, v176
	v_exp_f32_e32 v88, v88
	v_add_f32_e32 v176, v84, v176
	v_exp_f32_e32 v89, v89
	v_add_f32_e32 v176, v85, v176
	v_exp_f32_e32 v90, v90
	v_add_f32_e32 v176, v86, v176
	v_exp_f32_e32 v91, v91
	v_add_f32_e32 v176, v87, v176
	v_exp_f32_e32 v92, v92
	v_add_f32_e32 v176, v88, v176
	v_exp_f32_e32 v93, v177
	v_add_f32_e32 v176, v89, v176
	v_exp_f32_e32 v94, v178
	v_add_f32_e32 v176, v90, v176
	v_add_f32_e32 v176, v91, v176
	v_add_f32_e32 v176, v92, v176
	v_add_f32_e32 v176, v93, v176
	v_add_f32_e32 v176, v94, v176
	v_add_f32_e32 v236, v95, v176
	v_mov_b32_e32 v237, v236
	v_cvt_pk_bf16_f32 v176, v64, v65
	v_cvt_pk_bf16_f32 v177, v66, v67
	v_cvt_pk_bf16_f32 v178, v68, v69
	v_cvt_pk_bf16_f32 v179, v70, v71
	v_cvt_pk_bf16_f32 v188, v88, v89
	v_cvt_pk_bf16_f32 v189, v90, v91
	v_cvt_pk_bf16_f32 v190, v92, v93
	v_cvt_pk_bf16_f32 v191, v94, v95
	v_permlane32_swap_b32_e32 v236, v237
	v_permlane32_swap_b32_e32 v176, v178
	v_permlane32_swap_b32_e32 v177, v179
	v_permlane32_swap_b32_e32 v188, v190
	v_permlane32_swap_b32_e32 v189, v191
	v_cvt_pk_bf16_f32 v180, v72, v73
	v_cvt_pk_bf16_f32 v181, v74, v75
	v_cvt_pk_bf16_f32 v182, v76, v77
	v_cvt_pk_bf16_f32 v183, v78, v79
	s_nop 0
	v_permlane32_swap_b32_e32 v180, v182
	v_permlane32_swap_b32_e32 v181, v183
	v_cvt_pk_bf16_f32 v184, v80, v81
	v_cvt_pk_bf16_f32 v185, v82, v83
	v_cvt_pk_bf16_f32 v186, v84, v85
	v_cvt_pk_bf16_f32 v187, v86, v87
	s_nop 0
	v_permlane32_swap_b32_e32 v184, v186
	v_permlane32_swap_b32_e32 v185, v187
	s_add_i32 s40, s80, 1
	s_cmp_lt_u32 s40, s79
	s_cselect_b64 s[42:43], -1, 0
	s_cmp_ge_u32 s40, s79
	s_cbranch_scc1 .Lmy_B326
	v_add_u32_e32 v160, 64, v212
	v_add_u32_e32 v162, 0x60, v212
	v_ashrrev_i32_e32 v161, 31, v160
	v_ashrrev_i32_e32 v163, 31, v162
	v_lshlrev_b64 v[168:169], 8, v[160:161]
	v_lshlrev_b64 v[170:171], 8, v[162:163]
	v_lshl_add_u64 v[160:161], v[208:209], 0, v[168:169]
	v_lshl_add_u64 v[164:165], v[208:209], 0, v[170:171]
	v_lshl_add_u64 v[168:169], v[210:211], 0, v[168:169]
	v_lshl_add_u64 v[172:173], v[210:211], 0, v[170:171]
	global_load_dwordx4 v[160:163], v[160:161], off
	s_nop 0
	global_load_dwordx4 v[164:167], v[164:165], off
	s_nop 0
	global_load_dwordx4 v[168:171], v[168:169], off
	s_nop 0
	global_load_dwordx4 v[172:175], v[172:173], off

; __device__ __forceinline__ void partialSM(f32x16& p0, f32x16& p1, float& m_reg, float& mn, float& alpha) {
;     float pmax = p0[0]; for (int r = 1; r < 16; ++r) pmax = fmaxf(pmax, p0[r]); for (int r = 0; r < 16; ++r) pmax = fmaxf(pmax, p1[r]);
;     { auto rr = __builtin_amdgcn_permlane32_swap(__float_as_uint(pmax), __float_as_uint(pmax), false, false);
;       pmax = fmaxf(__uint_as_float(rr[0]), __uint_as_float(rr[1])); }
;     constexpr float C2 = 1.4426950408889634f * SCALE;
;     if (__builtin_expect(__all((pmax - m_reg) * SCALE <= THR), 1)) { mn = m_reg; alpha = 1.f; }
;     else { mn = fmaxf(m_reg, pmax); alpha = __builtin_amdgcn_exp2f((m_reg - mn) * C2); m_reg = mn; }
; template <int KB>
; __device__ __forceinline__ void qkt(f32x16& p0, f32x16& p1, const char* K_lds, int r32, int hi, const bf16x8* qr) {
;     p0 = f32x16{}; p1 = f32x16{};
;     const char* kb[4];
; #pragma unroll
;     for (int dd = 0; dd < 4; ++dd) kb[dd] = K_lds + KB * SHM_K + KSWZ(r32, (dd * 16 + hi * 8) * 2);
; #pragma unroll
;     for (int d0 = 0; d0 < 8; ++d0) { const char* a = kb[d0 & 3] + (d0 >> 2) * 128;
;         bf16x8 b0 = *reinterpret_cast<const bf16x8*>(a);
;         bf16x8 b1 = *reinterpret_cast<const bf16x8*>(a + 32 * 256);
;         p0 = __builtin_amdgcn_mfma_f32_32x32x16_bf16(b0, qr[d0], p0, 0, 0, 0);
;         p1 = __builtin_amdgcn_mfma_f32_32x32x16_bf16(b1, qr[d0], p1, 0, 0, 0); }
; }
.Lmy_B_skip_w2:
	v_mfma_f32_32x32x16_bf16 v[16:31], v[176:179], v[238:241], v[16:31]
	v_mfma_f32_32x32x16_bf16 v[16:31], v[180:183], v[242:245], v[16:31]
	v_mfma_f32_32x32x16_bf16 v[16:31], v[184:187], v[246:249], v[16:31]
	v_mfma_f32_32x32x16_bf16 v[16:31], v[188:191], v[250:253], v[16:31]
	v_xor_b32_e32 v250, 0x80, v201
	v_xor_b32_e32 v251, 0x80, v230
	v_xor_b32_e32 v252, 0x80, v229
	v_xor_b32_e32 v253, 0x80, v207
	ds_read_b128 v[96:99], v201 offset:32768
	ds_read_b128 v[100:103], v201 offset:40960
	ds_read_b128 v[180:183], v230 offset:32768
	ds_read_b128 v[184:187], v230 offset:40960
	s_waitcnt lgkmcnt(3)
	v_mfma_f32_32x32x16_bf16 v[112:127], v[96:99], v[156:159], 0
	s_waitcnt lgkmcnt(2)
	v_mfma_f32_32x32x16_bf16 v[96:111], v[100:103], v[156:159], 0
	s_waitcnt lgkmcnt(1)
	v_mfma_f32_32x32x16_bf16 v[112:127], v[180:183], v[152:155], v[112:127]
	s_waitcnt lgkmcnt(0)
	v_mfma_f32_32x32x16_bf16 v[96:111], v[184:187], v[152:155], v[96:111]
	ds_read_b128 v[180:183], v229 offset:32768
	ds_read_b128 v[184:187], v229 offset:40960
	s_waitcnt lgkmcnt(1)
	v_mfma_f32_32x32x16_bf16 v[112:127], v[180:183], v[148:151], v[112:127]
	s_waitcnt lgkmcnt(0)
	v_mfma_f32_32x32x16_bf16 v[96:111], v[184:187], v[148:151], v[96:111]
	ds_read_b128 v[180:183], v207 offset:32768
	ds_read_b128 v[184:187], v207 offset:40960
	s_waitcnt lgkmcnt(1)
	v_mfma_f32_32x32x16_bf16 v[112:127], v[180:183], v[144:147], v[112:127]
	s_waitcnt lgkmcnt(0)
	v_mfma_f32_32x32x16_bf16 v[96:111], v[184:187], v[144:147], v[96:111]
	ds_read_b128 v[180:183], v250 offset:32768
	ds_read_b128 v[184:187], v250 offset:40960
	s_waitcnt lgkmcnt(1)
	v_mfma_f32_32x32x16_bf16 v[112:127], v[180:183], v[140:143], v[112:127]
	s_waitcnt lgkmcnt(0)
	v_mfma_f32_32x32x16_bf16 v[96:111], v[184:187], v[140:143], v[96:111]
	ds_read_b128 v[180:183], v251 offset:32768
	ds_read_b128 v[184:187], v251 offset:40960
	s_waitcnt lgkmcnt(1)
	v_mfma_f32_32x32x16_bf16 v[112:127], v[180:183], v[136:139], v[112:127]
	s_waitcnt lgkmcnt(0)
	v_mfma_f32_32x32x16_bf16 v[96:111], v[184:187], v[136:139], v[96:111]
	ds_read_b128 v[180:183], v252 offset:32768
	ds_read_b128 v[184:187], v252 offset:40960
	s_waitcnt lgkmcnt(1)
	v_mfma_f32_32x32x16_bf16 v[112:127], v[180:183], v[132:135], v[112:127]
	s_waitcnt lgkmcnt(0)
	v_mfma_f32_32x32x16_bf16 v[96:111], v[184:187], v[132:135], v[96:111]
	ds_read_b128 v[180:183], v253 offset:32768
	ds_read_b128 v[184:187], v253 offset:40960
	s_waitcnt lgkmcnt(1)
	v_mfma_f32_32x32x16_bf16 v[112:127], v[180:183], v[128:131], v[112:127]
	s_waitcnt lgkmcnt(0)
	v_mfma_f32_32x32x16_bf16 v[96:111], v[184:187], v[128:131], v[96:111]
	s_nop 15
	s_nop 0
	s_cmp_gt_i32 s50, s49
	s_cbranch_scc0 .Lmy_B_nomask2
	v_mov_b32_e32 v96, v220
	v_mov_b32_e32 v97, v220
	v_mov_b32_e32 v98, v220
	v_mov_b32_e32 v99, v220
	v_mov_b32_e32 v100, v220
	v_mov_b32_e32 v101, v220
	v_mov_b32_e32 v102, v220
	v_mov_b32_e32 v103, v220
	v_mov_b32_e32 v104, v220
	v_mov_b32_e32 v105, v220
	v_mov_b32_e32 v106, v220
	v_mov_b32_e32 v107, v220
	v_mov_b32_e32 v108, v220
	v_mov_b32_e32 v109, v220
	v_mov_b32_e32 v110, v220
	v_mov_b32_e32 v111, v220
	v_mov_b32_e32 v112, v220
	v_mov_b32_e32 v113, v220
	v_mov_b32_e32 v114, v220
	v_mov_b32_e32 v115, v220
	v_mov_b32_e32 v116, v220
	v_mov_b32_e32 v117, v220
	v_mov_b32_e32 v118, v220
	v_mov_b32_e32 v119, v220
	v_mov_b32_e32 v120, v220
	v_mov_b32_e32 v121, v220
	v_mov_b32_e32 v122, v220
	v_mov_b32_e32 v123, v220
	v_mov_b32_e32 v124, v220
	v_mov_b32_e32 v125, v220
	v_mov_b32_e32 v126, v220
	v_mov_b32_e32 v127, v220
.Lmy_B_nomask2:
	v_max_f32_e32 v176, v113, v113
	v_max_f32_e32 v177, v112, v112
	v_max_f32_e32 v176, v177, v176
	s_nop 0
	v_max3_f32 v176, v176, v114, v115
	v_max3_f32 v176, v176, v116, v117
	v_max3_f32 v176, v176, v118, v119
	v_max3_f32 v176, v176, v120, v121
	v_max3_f32 v176, v176, v122, v123
	v_max3_f32 v176, v176, v124, v125
	v_max3_f32 v176, v176, v126, v127
	v_max3_f32 v176, v176, v96, v97
	s_nop 0
	v_max3_f32 v176, v176, v98, v99
	v_max3_f32 v176, v176, v100, v101
	v_max3_f32 v176, v176, v102, v103
	v_max3_f32 v176, v176, v104, v105
	v_max3_f32 v176, v176, v106, v107
	v_max3_f32 v176, v176, v108, v109
	v_max3_f32 v176, v176, v110, v111
	v_mov_b32_e32 v177, v176
	s_nop 0
	s_nop 0
	v_permlane32_swap_b32_e32 v176, v177
	v_max_f32_e32 v177, v177, v177
	v_max_f32_e32 v176, v176, v176
	v_max_f32_e32 v176, v176, v177
	v_sub_f32_e32 v177, v176, v235
	v_mul_f32_e32 v177, 0x3db504f3, v177
	v_cmp_ge_f32_e32 vcc, s67, v177
	s_cmp_eq_u64 vcc, exec
	s_cselect_b64 s[40:41], -1, 0

; #define PG8_WAIT_V(n) asm volatile("s_waitcnt vmcnt(" #n ")" ::: "memory")
; #define PG8_BAR __builtin_amdgcn_s_barrier()
; template <class Epi, class Sched, bool ALIGN_EPI = false, bool SP2 = false>
; __device__ __forceinline__ void gemm_phase(PG8_LAS unsigned char* lds, const Gemm g, const Sched& S, const Epi& E) {
;     int tid_ = threadIdx.x; asm volatile("" : "+v"(tid_));
;     const int tid = tid_, wid = __builtin_amdgcn_readfirstlane(tid >> 6), lane = tid & 63, wr = wid >> 2, wc = wid & 3, fr = lane & 15, fq = lane >> 4;
;     const int K = g.K, nt = K / BK;
;     unsigned voffA[2], voffB[2];
; #pragma unroll
;     for (int i = 0; i < 2; ++i) { int R, C; stage_rc(tid * 16 + i * 8192, R, C); const int Rb = Epi::PERM ? ((R & ~31) + perm32(R & 31)) : R;
;         voffA[i] = (unsigned)(R * K + C) * 2u; voffB[i] = (unsigned)(Rb * K + C) * 2u; }
;     const size_t kstep = (size_t)(BK * 2);
;     const size_t hstep = (size_t)HALF * K * 2;
;     const size_t tstep = 2 * hstep;
;     const unsigned ldsw = (unsigned)wid * 1024u;
;     const int aoff = lds_byte(wr * 64 + fr, fq * 8), boff = lds_byte(wc * 32 + fr, fq * 8);
;     ...
;     Unit cur, nxt; int ui = 0;
;     if (!S.next(0, cur)) return;
;     f32x4 acc[2][2][4][2];
; #pragma unroll
;     for (int a = 0; a < 2; ++a)
; #pragma unroll
;         for (int b = 0; b < 2; ++b)
; #pragma unroll
;             for (int m = 0; m < 4; ++m)
; #pragma unroll
;                 for (int n = 0; n < 2; ++n) acc[a][b][m][n] = (f32x4){0.f, 0.f, 0.f, 0.f};
;     bf16x8 At[4][2], B0[2][2], B1[2][2];
;     const char* cA = (const char*)g.A + (size_t)cur.pm * tstep; const char* cB = (const char*)g.Bt + (size_t)cur.pn * tstep;
;     S.a_ready(cur);
;     if constexpr (SP2) {
;         PG8_STAGE(PG8_SB(0, 0), cB, voffB); PG8_STAGE(PG8_SB(0, 1), cB + hstep, voffB); PG8_STAGE(PG8_SA(0, 0), cA, voffA); PG8_STAGE(PG8_SA(0, 1), cA + hstep, voffA);
;         if (wr == 1) PG8_BAR;
;         PG8_WAIT_V(2); PG8_BAR;
;         PG8_STAGE(PG8_SB(1, 0), cB + kstep, voffB); PG8_STAGE(PG8_SA(1, 0), cA + kstep, voffA); PG8_STAGE(PG8_SB(1, 1), cB + hstep + kstep, voffB);
;         PG8_WAIT_V(6); PG8_BAR;
;     } else {
;         PG8_STAGE(PG8_SB(0, 0), cB, voffB); PG8_STAGE(PG8_SA(0, 0), cA, voffA); PG8_STAGE(PG8_SB(0, 1), cB + hstep, voffB); PG8_STAGE(PG8_SA(0, 1), cA + hstep, voffA);
;         if (wr == 1) PG8_BAR;
;         PG8_WAIT_V(4); PG8_BAR;
.LBB0_540:
	s_or_b64 exec, exec, s[14:15]
	s_nop 0
	s_nop 0
	s_nop 0
	s_nop 0
	s_nop 0
	s_nop 0
	s_nop 0
	s_nop 0
	s_nop 0
	s_nop 0
	s_nop 0
	s_nop 0
	s_nop 0
	s_nop 0
	s_nop 0
	s_nop 0
	s_nop 0
	s_nop 0
	s_nop 0
	s_cmpk_lt_i32 s2, 0x400
	s_mov_b64 s[22:23], s[0:1]
	s_mov_b64 s[16:17], s[0:1]
	s_mov_b64 s[24:25], s[0:1]
	s_mov_b64 s[18:19], s[0:1]
	s_mov_b64 s[14:15], s[0:1]
	s_waitcnt lgkmcnt(0)
	s_barrier
	s_cselect_b64 s[48:49], -1, 0
	s_lshr_b32 s13, s33, 29
	s_add_i32 s13, s2, s13
	s_load_dwordx2 s[14:15], s[14:15], 0xc8
	s_ashr_i32 s56, s13, 3
	s_and_b32 s13, s13, -8
	s_load_dwordx2 s[20:21], s[16:17], 0xc8
	s_nop 0
	s_load_dwordx2 s[18:19], s[18:19], 0xc8
	s_mov_b64 s[16:17], s[0:1]
	s_sub_i32 s59, s2, s13
	s_cmp_lt_i32 s59, 0
	s_load_dwordx2 s[16:17], s[16:17], 0xc8
	s_cselect_b64 s[42:43], -1, 0
	s_lshl_b32 s57, s59, 7
	s_waitcnt lgkmcnt(0)
	s_add_u32 s14, s14, 0x2f800000
	s_addc_u32 s15, s15, 0
	s_waitcnt vmcnt(27)
	v_mov_b32_e32 v14, v216
	s_cmpk_gt_i32 s2, 0x3ff
	s_mul_i32 s58, s59, 0x81
	s_nop 0
	v_readfirstlane_b32 s28, v14
	s_cbranch_scc1 .LBB0_560
	v_lshlrev_b32_e32 v0, 4, v14
	v_add_u32_e32 v1, 0x2000, v0
	v_ashrrev_i32_e32 v2, 31, v1
	v_lshrrev_b32_e32 v2, 22, v2
	v_add_u32_e32 v2, v1, v2
	v_ashrrev_i32_e32 v8, 10, v2
	v_mul_i32_i24_e32 v2, 0x400, v8
	v_sub_u32_e32 v1, v1, v2
	v_lshrrev_b32_e32 v2, 4, v1
	v_bitop3_b32 v1, v2, v1, 32 bitop3:0x6c
	v_ashrrev_i32_e32 v2, 31, v1
	s_load_dwordx2 s[22:23], s[22:23], 0xc8
	s_nop 0
	s_load_dwordx2 s[24:25], s[24:25], 0xc8
	v_lshrrev_b32_e32 v2, 26, v2
	v_add_u32_e32 v2, v1, v2
	v_lshlrev_b32_e32 v3, 3, v8
	v_ashrrev_i32_e32 v9, 6, v2
	v_and_b32_e32 v3, -16, v3
	v_add_u32_e32 v3, v9, v3
	s_waitcnt lgkmcnt(0)
	s_add_u32 s13, s22, 0x3b800000
	v_and_b32_e32 v4, 3, v9
	s_mov_b32 s22, 0x1fffe0
	v_lshrrev_b32_e32 v5, 2, v3
	v_lshlrev_b32_e32 v6, 1, v3
	v_and_b32_e32 v2, 0xc0, v2
	v_and_or_b32 v4, v3, s22, v4
	v_and_b32_e32 v5, 4, v5
	v_and_b32_e32 v6, 24, v6
	v_sub_u32_e32 v1, v1, v2
	v_mov_b32_e32 v2, 1
	v_or3_b32 v4, v4, v5, v6
	v_lshlrev_b32_e32 v5, 5, v8
	v_ashrrev_i16_sdwa v1, v2, sext(v1) dst_sel:DWORD dst_unused:UNUSED_PAD src0_sel:DWORD src1_sel:BYTE_0
	v_and_b32_e32 v5, 32, v5
	v_bfe_i32 v10, v1, 0, 16
	v_add_lshl_u32 v1, v5, v10, 1
	s_waitcnt vmcnt(6)
	v_lshl_add_u32 v152, v4, 11, v1
	v_lshl_add_u32 v154, v3, 11, v1
	v_bfe_i32 v1, v14, 27, 1
	v_lshrrev_b32_e32 v1, 22, v1
	v_add_u32_e32 v1, v0, v1
	v_and_b32_e32 v1, 0xfffffc00, v1
	v_sub_u32_e32 v0, v0, v1
	v_lshrrev_b32_e32 v1, 4, v0
	v_ashrrev_i32_e32 v3, 31, v14
	v_bitop3_b32 v0, v1, v0, 32 bitop3:0x6c
	v_lshrrev_b32_e32 v3, 26, v3
	v_ashrrev_i32_e32 v1, 31, v0
	v_add_u32_e32 v3, v14, v3
	s_addc_u32 s47, s23, 0
	v_lshrrev_b32_e32 v1, 26, v1
	v_ashrrev_i32_e32 v12, 6, v3
	s_add_u32 s60, s24, 0x2600000
	v_add_u32_e32 v1, v0, v1
	v_lshlrev_b32_e32 v3, 3, v12
	s_addc_u32 s61, s25, 0
	s_ashr_i32 s26, s28, 6
	v_ashrrev_i32_e32 v11, 6, v1
	v_and_b32_e32 v3, -16, v3
	s_ashr_i32 s27, s28, 8
	s_lshl_b32 s62, s26, 10
	v_add_u32_e32 v3, v11, v3
	v_and_b32_e32 v4, 3, v11
	v_and_or_b32 v4, v3, s22, v4
	s_and_b64 s[22:23], s[42:43], exec
	s_cselect_b32 s22, s58, s57
	s_add_i32 s22, s22, s56
	s_ashr_i32 s23, s22, 31
	s_lshr_b32 s23, s23, 27
	s_add_i32 s23, s22, s23
	s_ashr_i32 s24, s23, 5
	s_and_b32 s23, s23, 0xffe0
	s_sub_i32 s22, s22, s23
	s_bfe_i32 s23, s22, 0x80000
	s_bfe_u32 s23, s23, 0x2000d
	s_add_i32 s23, s22, s23
	s_lshl_b32 s25, s24, 2
	s_bfe_i32 s24, s23, 0x80000
	s_and_b32 s23, s23, 0xfc
	s_sub_i32 s22, s22, s23
	s_sext_i32_i16 s24, s24
	s_sext_i32_i8 s22, s22
	v_lshrrev_b32_e32 v5, 2, v3
	v_lshlrev_b32_e32 v6, 1, v3
	v_and_b32_e32 v1, 0xc0, v1
	s_lshr_b32 s24, s24, 2
	s_add_i32 s44, s25, s22
	v_and_b32_e32 v5, 4, v5
	v_and_b32_e32 v6, 24, v6
	v_sub_u32_e32 v0, v0, v1
	s_ashr_i32 s45, s44, 31
	s_bfe_i64 s[30:31], s[24:25], 0x100000
	v_or3_b32 v4, v4, v5, v6
	v_lshlrev_b32_e32 v5, 5, v12
	v_ashrrev_i16_sdwa v0, v2, sext(v0) dst_sel:DWORD dst_unused:UNUSED_PAD src0_sel:DWORD src1_sel:BYTE_0
	s_lshl_b64 s[22:23], s[44:45], 19
	s_lshl_b64 s[30:31], s[30:31], 19
	v_and_b32_e32 v5, 32, v5
	v_bfe_i32 v13, v0, 0, 16
	s_add_u32 s52, s60, s30
	v_add_lshl_u32 v0, v5, v13, 1
	s_addc_u32 s53, s61, s31
	s_add_i32 s63, s62, 0
	v_lshl_add_u32 v156, v4, 11, v0
	s_add_i32 m0, s63, 0x10000
	v_lshl_add_u32 v158, v3, 11, v0
	global_load_lds_dwordx4 v156, s[52:53]
	s_add_i32 m0, s63, 0x12000
	s_add_u32 s30, s52, 0x40000
	global_load_lds_dwordx4 v152, s[52:53]
	s_addc_u32 s31, s53, 0
	s_add_i32 m0, s63, 0x14000
	v_mov_b32_e32 v157, 0
	global_load_lds_dwordx4 v156, s[30:31]
	s_add_i32 m0, s63, 0x16000
	s_add_u32 s50, s13, s22
	s_addc_u32 s51, s47, s23
	s_add_i32 s64, s63, 0x2000
	global_load_lds_dwordx4 v152, s[30:31]
	s_mov_b32 m0, s63
	s_add_u32 s22, s50, 0x40000
	global_load_lds_dwordx4 v158, s[50:51]
	s_mov_b32 m0, s64
	s_addc_u32 s23, s51, 0
	s_add_i32 s65, s63, 0x4000
	global_load_lds_dwordx4 v154, s[50:51]
	s_mov_b32 m0, s65
	s_add_i32 s66, s63, 0x6000
	global_load_lds_dwordx4 v158, s[22:23]
	s_mov_b32 m0, s66
	v_mov_b32_e32 v153, v157
	global_load_lds_dwordx4 v154, s[22:23]
	v_mov_b32_e32 v159, v157
	v_mov_b32_e32 v155, v157
	s_cmp_eq_u32 s27, 1
	v_lshl_add_u64 v[6:7], s[52:53], 0, v[156:157]
	v_lshl_add_u64 v[4:5], s[52:53], 0, v[152:153]
	v_lshl_add_u64 v[0:1], s[50:51], 0, v[158:159]
	s_cselect_b64 s[22:23], -1, 0
	s_cmp_lg_u32 s27, 1
	v_lshl_add_u64 v[2:3], s[50:51], 0, v[154:155]
	s_cbranch_scc1 .LBB0_543
	s_barrier
